# LayerNorm phases: wave all-reduce via DPP adds and permlane16/32 swaps instead of six ds_bpermute round trips
# speedup vs baseline: 1.0024x; 1.0024x over previous
; __device__ __forceinline__ float wave_sum(float v) {
; #pragma unroll
;     for (int o = 1; o < 64; o <<= 1) v += __shfl_xor(v, o);
;     return v;
; }
; template <bool STATS>
; __device__ __forceinline__ void ln_row(const float* xin, float* xout, bf16_t* bout, const float* __restrict__ g, const float* __restrict__ b, int lane, f32x2* st) {
;     f32x4 v[8]; float s = 0.f;
; #pragma unroll
;     for (int j = 0; j < 8; ++j) { v[j] = *(const f32x4*)(xin + (lane + 64 * j) * 4); s += (v[j].x + v[j].y) + (v[j].z + v[j].w); }
;     const float mean = wave_sum(s) * (1.f / DM); float s2 = 0.f;
; #pragma unroll
;     for (int j = 0; j < 8; ++j) { v[j] = v[j] - mean; s2 += (v[j].x * v[j].x + v[j].y * v[j].y) + (v[j].z * v[j].z + v[j].w * v[j].w); }
;     const float rstd = 1.f / sqrtf(wave_sum(s2) * (1.f / DM) + 1e-5f);
;     if constexpr (STATS) { if (lane == 0) *st = (f32x2){mean, rstd}; }
.LBB0_891:
	global_load_dwordx4 v[36:39], v[64:65], off offset:-4096
	global_load_dwordx4 v[32:35], v[64:65], off offset:-3072
	global_load_dwordx4 v[28:31], v[64:65], off offset:-2048
	global_load_dwordx4 v[24:27], v[64:65], off offset:-1024
	global_load_dwordx4 v[20:23], v[64:65], off
	global_load_dwordx4 v[16:19], v[64:65], off offset:1024
	global_load_dwordx4 v[12:15], v[64:65], off offset:2048
	global_load_dwordx4 v[8:11], v[64:65], off offset:3072
	s_waitcnt vmcnt(7)
	v_mov_b32_e32 v74, v36
	s_waitcnt vmcnt(6)
	v_mov_b32_e32 v75, v32
	v_mov_b32_e32 v76, v37
	v_mov_b32_e32 v77, v33
	v_mov_b32_e32 v78, v38
	v_mov_b32_e32 v79, v34
	v_mov_b32_e32 v80, v39
	v_mov_b32_e32 v81, v35
	s_waitcnt vmcnt(5)
	v_mov_b32_e32 v82, v29
	v_mov_b32_e32 v83, v30
	v_mov_b32_e32 v84, v28
	v_mov_b32_e32 v85, v31
	v_pk_add_f32 v[74:75], v[74:75], v[76:77]
	v_pk_add_f32 v[76:77], v[78:79], v[80:81]
	v_pk_add_f32 v[78:79], v[82:83], v[84:85]
	v_pk_add_f32 v[74:75], v[74:75], v[76:77]
	v_pk_add_f32 v[76:77], v[78:79], v[78:79] op_sel:[0,1] op_sel_hi:[1,0]
	v_add_f32_e32 v40, 0, v74
	s_waitcnt vmcnt(4)
	v_add_f32_e32 v86, v24, v25
	v_add_f32_e32 v88, v26, v27
	s_waitcnt vmcnt(3)
	v_mov_b32_e32 v91, v20
	v_mov_b32_e32 v87, v22
	v_mov_b32_e32 v89, v23
	v_mov_b32_e32 v77, v21
	v_add_f32_e32 v90, v40, v75
	s_waitcnt vmcnt(2)
	v_mov_b32_e32 v92, v17
	v_mov_b32_e32 v93, v18
	v_mov_b32_e32 v94, v16
	v_mov_b32_e32 v95, v19
	v_pk_add_f32 v[80:81], v[86:87], v[88:89]
	v_pk_add_f32 v[74:75], v[90:91], v[76:77]
	v_pk_add_f32 v[82:83], v[92:93], v[94:95]
	v_pk_add_f32 v[74:75], v[74:75], v[80:81]
	v_pk_add_f32 v[78:79], v[82:83], v[82:83] op_sel:[0,1] op_sel_hi:[1,0]
	v_pk_add_f32 v[74:75], v[74:75], v[74:75] op_sel:[0,1] op_sel_hi:[1,0]
	s_waitcnt vmcnt(1)
	v_add_f32_e32 v96, v12, v13
	v_add_f32_e32 v98, v14, v15
	s_waitcnt vmcnt(0)
	v_mov_b32_e32 v97, v10
	v_mov_b32_e32 v99, v11
	v_mov_b32_e32 v79, v9
	v_mov_b32_e32 v75, v8
	v_pk_add_f32 v[84:85], v[96:97], v[98:99]
	v_pk_add_f32 v[74:75], v[74:75], v[78:79]
	s_nop 0
	v_pk_add_f32 v[74:75], v[74:75], v[84:85]
	s_nop 0
	v_add_f32_e32 v40, v74, v75
	s_nop 1
	v_add_f32_dpp v40, v40, v40 quad_perm:[1,0,3,2] row_mask:0xf bank_mask:0xf
	s_nop 1
	v_add_f32_dpp v40, v40, v40 quad_perm:[2,3,0,1] row_mask:0xf bank_mask:0xf
	s_nop 1
	v_add_f32_dpp v40, v40, v40 row_half_mirror row_mask:0xf bank_mask:0xf
	s_nop 1
	v_add_f32_dpp v40, v40, v40 row_mirror row_mask:0xf bank_mask:0xf
	v_mov_b32_e32 v74, v40
	s_nop 1
	v_permlane16_swap_b32_e32 v40, v74
	v_add_f32_e32 v40, v40, v74
	v_mov_b32_e32 v74, v40
	s_nop 1
	v_permlane32_swap_b32_e32 v40, v74
	v_add_f32_e32 v74, v40, v74
	v_fmamk_f32 v39, v74, 0xba000000, v39
	v_fmamk_f32 v37, v74, 0xba000000, v37
	v_fmamk_f32 v35, v74, 0xba000000, v35
	v_fmamk_f32 v33, v74, 0xba000000, v33
	v_fmamk_f32 v38, v74, 0xba000000, v38
	v_fmac_f32_e32 v36, 0xba000000, v74
	v_fmamk_f32 v34, v74, 0xba000000, v34
	v_fmac_f32_e32 v32, 0xba000000, v74
	v_fmamk_f32 v31, v74, 0xba000000, v31
	v_fmamk_f32 v29, v74, 0xba000000, v29
	v_mul_f32_e32 v40, v37, v37
	v_mul_f32_e32 v75, v39, v39
	v_mul_f32_e32 v76, v33, v33
	v_mul_f32_e32 v77, v35, v35
	v_fmamk_f32 v30, v74, 0xba000000, v30
	v_fmac_f32_e32 v28, 0xba000000, v74
	v_fmamk_f32 v27, v74, 0xba000000, v27
	v_fmamk_f32 v25, v74, 0xba000000, v25
	v_mul_f32_e32 v78, v29, v29
	v_mul_f32_e32 v79, v31, v31
	v_fmac_f32_e32 v40, v36, v36
	v_fmac_f32_e32 v75, v38, v38
	v_fmac_f32_e32 v76, v32, v32
	v_fmac_f32_e32 v77, v34, v34
	v_fmamk_f32 v26, v74, 0xba000000, v26
	v_fmac_f32_e32 v24, 0xba000000, v74
	v_fmamk_f32 v23, v74, 0xba000000, v23
	v_fmamk_f32 v21, v74, 0xba000000, v21
	v_mul_f32_e32 v80, v25, v25
	v_mul_f32_e32 v81, v27, v27
	v_fmac_f32_e32 v78, v28, v28
	v_fmac_f32_e32 v79, v30, v30
	v_add_f32_e32 v40, v40, v75
	v_add_f32_e32 v75, v76, v77
	v_fmamk_f32 v22, v74, 0xba000000, v22
	v_fmac_f32_e32 v20, 0xba000000, v74
	v_fmamk_f32 v19, v74, 0xba000000, v19
	v_fmamk_f32 v17, v74, 0xba000000, v17
	v_mul_f32_e32 v82, v21, v21
	v_mul_f32_e32 v83, v23, v23
	v_fmac_f32_e32 v80, v24, v24
	v_fmac_f32_e32 v81, v26, v26
	v_add_f32_e32 v76, v78, v79
	v_add_f32_e32 v40, v40, v75
	v_fmamk_f32 v18, v74, 0xba000000, v18
	v_fmac_f32_e32 v16, 0xba000000, v74
	v_fmamk_f32 v15, v74, 0xba000000, v15
	v_fmamk_f32 v13, v74, 0xba000000, v13
	v_mul_f32_e32 v84, v17, v17
	v_mul_f32_e32 v85, v19, v19
	v_fmac_f32_e32 v82, v20, v20
	v_fmac_f32_e32 v83, v22, v22
	v_add_f32_e32 v77, v80, v81
	v_add_f32_e32 v40, v76, v40
	v_fmamk_f32 v14, v74, 0xba000000, v14
	v_fmac_f32_e32 v12, 0xba000000, v74
	v_fmamk_f32 v11, v74, 0xba000000, v11
	v_fmamk_f32 v9, v74, 0xba000000, v9
	v_mul_f32_e32 v86, v13, v13
	v_mul_f32_e32 v87, v15, v15
	v_fmac_f32_e32 v84, v16, v16
	v_fmac_f32_e32 v85, v18, v18
	v_add_f32_e32 v78, v82, v83
	v_add_f32_e32 v40, v77, v40
	v_fmamk_f32 v10, v74, 0xba000000, v10
	v_fmac_f32_e32 v8, 0xba000000, v74
	v_fmac_f32_e32 v86, v12, v12
	v_fmac_f32_e32 v87, v14, v14
	v_add_f32_e32 v79, v84, v85
	v_add_f32_e32 v40, v78, v40
	v_mul_f32_e32 v75, v9, v9
	v_mul_f32_e32 v76, v11, v11
	v_add_f32_e32 v80, v86, v87
	v_add_f32_e32 v40, v79, v40
	v_fmac_f32_e32 v75, v8, v8
	v_fmac_f32_e32 v76, v10, v10
	v_add_f32_e32 v40, v80, v40
	v_add_f32_e32 v75, v75, v76
	v_add_f32_e32 v40, v75, v40
	s_nop 1
	v_add_f32_dpp v40, v40, v40 quad_perm:[1,0,3,2] row_mask:0xf bank_mask:0xf
	s_nop 1
	v_add_f32_dpp v40, v40, v40 quad_perm:[2,3,0,1] row_mask:0xf bank_mask:0xf
	s_nop 1
	v_add_f32_dpp v40, v40, v40 row_half_mirror row_mask:0xf bank_mask:0xf
	s_nop 1
	v_add_f32_dpp v40, v40, v40 row_mirror row_mask:0xf bank_mask:0xf
	v_mov_b32_e32 v75, v40
	s_nop 1
	v_permlane16_swap_b32_e32 v40, v75
	v_add_f32_e32 v40, v40, v75
	v_mov_b32_e32 v75, v40
	s_nop 1
	v_permlane32_swap_b32_e32 v40, v75
	v_add_f32_e32 v40, v40, v75
	v_fmamk_f32 v40, v40, 0x3a000000, v72
	v_mul_f32_e32 v75, 0x4f800000, v40
	v_cmp_gt_f32_e32 vcc, s20, v40
	s_nop 1
	v_cndmask_b32_e32 v40, v40, v75, vcc
	v_sqrt_f32_e32 v75, v40
	s_nop 0
	v_add_u32_e32 v76, -1, v75
	v_add_u32_e32 v77, 1, v75
	v_fma_f32 v78, -v76, v75, v40
	v_fma_f32 v79, -v77, v75, v40
	v_cmp_ge_f32_e64 s[10:11], 0, v78
	s_nop 1
	v_cndmask_b32_e64 v75, v75, v76, s[10:11]
	v_cmp_lt_f32_e64 s[10:11], 0, v79
	s_nop 1
	v_cndmask_b32_e64 v75, v75, v77, s[10:11]
	v_mul_f32_e32 v76, 0x37800000, v75
	v_cndmask_b32_e32 v75, v75, v76, vcc
	v_cmp_class_f32_e32 vcc, v40, v73
	s_nop 1
	v_cndmask_b32_e32 v40, v75, v40, vcc
	v_div_scale_f32 v75, s[10:11], v40, v40, 1.0
	v_rcp_f32_e32 v76, v75
	v_div_scale_f32 v77, vcc, 1.0, v40, 1.0
	v_fma_f32 v78, -v75, v76, 1.0
	v_fmac_f32_e32 v76, v78, v76
	v_mul_f32_e32 v78, v77, v76
	v_fma_f32 v79, -v75, v78, v77
	v_fmac_f32_e32 v78, v79, v76
	v_fma_f32 v75, -v75, v78, v77
	v_div_fmas_f32 v75, v75, v76, v78
	v_div_fixup_f32 v40, v75, v40, 1.0
	s_and_saveexec_b64 s[10:11], s[8:9]
	s_cbranch_execz .LBB0_890
	s_add_u32 s24, s54, s0
	v_mul_f32_e32 v74, 0x3a000000, v74
	s_addc_u32 s25, s55, s1
	v_mov_b32_e32 v75, v40
	global_store_dwordx2 v41, v[74:75], s[24:25]
	s_branch .LBB0_890

; __device__ __forceinline__ float wave_sum(float v) {
; #pragma unroll
;     for (int o = 1; o < 64; o <<= 1) v += __shfl_xor(v, o);
;     return v;
; }
; template <bool STATS>
; __device__ __forceinline__ void ln_row(const float* xin, float* xout, bf16_t* bout, const float* __restrict__ g, const float* __restrict__ b, int lane, f32x2* st) {
;     f32x4 v[8]; float s = 0.f;
; #pragma unroll
;     for (int j = 0; j < 8; ++j) { v[j] = *(const f32x4*)(xin + (lane + 64 * j) * 4); s += (v[j].x + v[j].y) + (v[j].z + v[j].w); }
;     const float mean = wave_sum(s) * (1.f / DM); float s2 = 0.f;
; #pragma unroll
;     for (int j = 0; j < 8; ++j) { v[j] = v[j] - mean; s2 += (v[j].x * v[j].x + v[j].y * v[j].y) + (v[j].z * v[j].z + v[j].w * v[j].w); }
;     const float rstd = 1.f / sqrtf(wave_sum(s2) * (1.f / DM) + 1e-5f);
.LBB0_1091:
	global_load_dwordx4 v[92:95], v[96:97], off offset:-4096
	global_load_dwordx4 v[80:83], v[96:97], off offset:-3072
	global_load_dwordx4 v[88:91], v[96:97], off offset:-2048
	global_load_dwordx4 v[84:87], v[96:97], off offset:-1024
	global_load_dwordx4 v[76:79], v[96:97], off
	global_load_dwordx4 v[72:75], v[96:97], off offset:1024
	global_load_dwordx4 v[68:71], v[96:97], off offset:2048
	global_load_dwordx4 v[64:67], v[96:97], off offset:3072
	s_add_i32 s46, s46, s52
	s_cmp_gt_i32 s46, 0x9fff
	s_waitcnt vmcnt(7)
	v_mov_b32_e32 v106, v92
	s_waitcnt vmcnt(6)
	v_mov_b32_e32 v107, v80
	v_mov_b32_e32 v108, v93
	v_mov_b32_e32 v109, v81
	v_mov_b32_e32 v110, v94
	v_mov_b32_e32 v111, v82
	v_mov_b32_e32 v112, v95
	v_mov_b32_e32 v113, v83
	s_waitcnt vmcnt(5)
	v_mov_b32_e32 v114, v89
	v_mov_b32_e32 v115, v90
	v_mov_b32_e32 v116, v88
	v_mov_b32_e32 v117, v91
	v_pk_add_f32 v[106:107], v[106:107], v[108:109]
	v_pk_add_f32 v[108:109], v[110:111], v[112:113]
	v_pk_add_f32 v[110:111], v[114:115], v[116:117]
	v_pk_add_f32 v[106:107], v[106:107], v[108:109]
	v_pk_add_f32 v[108:109], v[110:111], v[110:111] op_sel:[0,1] op_sel_hi:[1,0]
	v_add_f32_e32 v106, 0, v106
	s_waitcnt vmcnt(4)
	v_add_f32_e32 v118, v84, v85
	v_add_f32_e32 v120, v86, v87
	s_waitcnt vmcnt(3)
	v_mov_b32_e32 v123, v76
	v_mov_b32_e32 v119, v78
	v_mov_b32_e32 v121, v79
	v_mov_b32_e32 v109, v77
	v_add_f32_e32 v122, v106, v107
	s_waitcnt vmcnt(2)
	v_mov_b32_e32 v124, v73
	v_mov_b32_e32 v125, v74
	v_mov_b32_e32 v126, v72
	v_mov_b32_e32 v127, v75
	v_pk_add_f32 v[112:113], v[118:119], v[120:121]
	v_pk_add_f32 v[106:107], v[122:123], v[108:109]
	v_pk_add_f32 v[114:115], v[124:125], v[126:127]
	v_pk_add_f32 v[106:107], v[106:107], v[112:113]
	v_pk_add_f32 v[110:111], v[114:115], v[114:115] op_sel:[0,1] op_sel_hi:[1,0]
	v_pk_add_f32 v[106:107], v[106:107], v[106:107] op_sel:[0,1] op_sel_hi:[1,0]
	s_waitcnt vmcnt(1)
	v_add_f32_e32 v128, v68, v69
	v_add_f32_e32 v130, v70, v71
	s_waitcnt vmcnt(0)
	v_mov_b32_e32 v129, v66
	v_mov_b32_e32 v131, v67
	v_mov_b32_e32 v111, v65
	v_mov_b32_e32 v107, v64
	v_pk_add_f32 v[116:117], v[128:129], v[130:131]
	v_pk_add_f32 v[106:107], v[106:107], v[110:111]
	s_nop 0
	v_pk_add_f32 v[106:107], v[106:107], v[116:117]
	s_nop 0
	v_add_f32_e32 v106, v106, v107
	s_nop 1
	v_add_f32_dpp v106, v106, v106 quad_perm:[1,0,3,2] row_mask:0xf bank_mask:0xf
	s_nop 1
	v_add_f32_dpp v106, v106, v106 quad_perm:[2,3,0,1] row_mask:0xf bank_mask:0xf
	s_nop 1
	v_add_f32_dpp v106, v106, v106 row_half_mirror row_mask:0xf bank_mask:0xf
	s_nop 1
	v_add_f32_dpp v106, v106, v106 row_mirror row_mask:0xf bank_mask:0xf
	v_mov_b32_e32 v107, v106
	s_nop 1
	v_permlane16_swap_b32_e32 v106, v107
	v_add_f32_e32 v106, v106, v107
	v_mov_b32_e32 v107, v106
	s_nop 1
	v_permlane32_swap_b32_e32 v106, v107
	v_add_f32_e32 v129, v106, v107
	v_fmamk_f32 v95, v129, 0xba000000, v95
	v_fmamk_f32 v93, v129, 0xba000000, v93
	v_fmamk_f32 v83, v129, 0xba000000, v83
	v_fmamk_f32 v81, v129, 0xba000000, v81
	v_fmamk_f32 v94, v129, 0xba000000, v94
	v_fmac_f32_e32 v92, 0xba000000, v129
	v_fmamk_f32 v82, v129, 0xba000000, v82
	v_fmac_f32_e32 v80, 0xba000000, v129
	v_fmamk_f32 v89, v129, 0xba000000, v89
	v_fmamk_f32 v88, v129, 0xba000000, v88
	v_fmamk_f32 v91, v129, 0xba000000, v91
	v_fmac_f32_e32 v90, 0xba000000, v129
	v_fmamk_f32 v109, v129, 0xba000000, v69
	v_fmamk_f32 v108, v129, 0xba000000, v68
	v_mov_b32_e32 v68, v93
	v_mov_b32_e32 v69, v81
	v_mov_b32_e32 v112, v95
	v_mov_b32_e32 v113, v83
	v_fmamk_f32 v107, v129, 0xba000000, v79
	v_fmamk_f32 v106, v129, 0xba000000, v78
	v_fmamk_f32 v111, v129, 0xba000000, v67
	v_fmamk_f32 v110, v129, 0xba000000, v66
	v_mov_b32_e32 v66, v92
	v_mov_b32_e32 v67, v80
	v_mov_b32_e32 v78, v94
	v_mov_b32_e32 v79, v82
	v_pk_mul_f32 v[114:115], v[90:91], v[90:91]
	v_pk_mul_f32 v[116:117], v[88:89], v[88:89]
	v_pk_mul_f32 v[68:69], v[68:69], v[68:69]
	v_pk_mul_f32 v[112:113], v[112:113], v[112:113]
	v_fmamk_f32 v84, v129, 0xba000000, v84
	v_fmac_f32_e32 v86, 0xba000000, v129
	v_pk_mov_b32 v[130:131], v[116:117], v[114:115] op_sel:[1,0]
	v_mov_b32_e32 v117, v115
	v_pk_fma_f32 v[66:67], v[66:67], v[66:67], v[68:69]
	v_pk_fma_f32 v[68:69], v[78:79], v[78:79], v[112:113]
	v_fmamk_f32 v85, v129, 0xba000000, v85
	v_fmamk_f32 v87, v129, 0xba000000, v87
	v_mul_f32_e32 v118, v84, v84
	v_mul_f32_e32 v120, v86, v86
	v_pk_add_f32 v[78:79], v[130:131], v[116:117]
	v_pk_add_f32 v[66:67], v[66:67], v[68:69]
	v_fmamk_f32 v77, v129, 0xba000000, v77
	v_fmac_f32_e32 v76, 0xba000000, v129
	v_fmamk_f32 v73, v129, 0xba000000, v73
	v_fmamk_f32 v72, v129, 0xba000000, v72
	v_fmamk_f32 v75, v129, 0xba000000, v75
	v_fmac_f32_e32 v74, 0xba000000, v129
	v_pk_fma_f32 v[114:115], v[84:85], v[84:85], v[118:119] op_sel_hi:[1,1,0]
	v_pk_fma_f32 v[118:119], v[86:87], v[86:87], v[120:121] op_sel_hi:[1,1,0]
	v_pk_add_f32 v[68:69], v[78:79], v[78:79] op_sel_hi:[0,1]
	v_pk_add_f32 v[66:67], v[66:67], v[66:67] op_sel_hi:[0,1]
	v_pk_mul_f32 v[122:123], v[74:75], v[74:75]
	v_pk_mul_f32 v[124:125], v[72:73], v[72:73]
	v_mul_f32_e32 v114, v76, v76
; __device__ __forceinline__ unsigned cvt_pk_bf16(float lo, float hi) { unsigned r; asm volatile("v_cvt_pk_bf16_f32 %0, %1, %2" : "=v"(r) : "v"(lo), "v"(hi)); return r; }
; __device__ __forceinline__ float wave_sum(float v) {
; #pragma unroll
;     for (int o = 1; o < 64; o <<= 1) v += __shfl_xor(v, o);
;     return v;
; }
; template <bool STATS>
; __device__ __forceinline__ void ln_row(const float* xin, float* xout, bf16_t* bout, const float* __restrict__ g, const float* __restrict__ b, int lane, f32x2* st) {
;     ...
;     const float mean = wave_sum(s) * (1.f / DM); float s2 = 0.f;
; #pragma unroll
;     for (int j = 0; j < 8; ++j) { v[j] = v[j] - mean; s2 += (v[j].x * v[j].x + v[j].y * v[j].y) + (v[j].z * v[j].z + v[j].w * v[j].w); }
;     const float rstd = 1.f / sqrtf(wave_sum(s2) * (1.f / DM) + 1e-5f);
;     if constexpr (STATS) { if (lane == 0) *st = (f32x2){mean, rstd}; }
; #pragma unroll
;     for (int j = 0; j < 8; ++j) { const int c = (lane + 64 * j) * 4; const f32x4 gg = *(const f32x4*)(g + c), bb = *(const f32x4*)(b + c);
;         const f32x4 o = v[j] * rstd * gg + bb;
;         if constexpr (STATS) { u32x2 w; w.x = cvt_pk_bf16(o.x, o.y); w.y = cvt_pk_bf16(o.z, o.w); *(u32x2*)(bout + c) = w; }
;         else *(f32x4*)(xout + c) = o; }
; }
	v_mul_f32_e32 v118, v77, v77
	v_mul_f32_e32 v68, v106, v106
	v_mul_f32_e32 v66, v107, v107
	v_fmac_f32_e32 v70, 0xba000000, v129
	v_pk_mov_b32 v[120:121], v[124:125], v[122:123] op_sel:[1,0]
	v_mov_b32_e32 v125, v123
	v_pk_add_f32 v[78:79], v[114:115], v[118:119]
	v_pk_add_f32 v[66:67], v[68:69], v[66:67]
	v_fmamk_f32 v71, v129, 0xba000000, v71
	v_mul_f32_e32 v126, v108, v108
	v_mul_f32_e32 v128, v70, v70
	v_pk_add_f32 v[112:113], v[120:121], v[124:125]
	v_pk_add_f32 v[66:67], v[78:79], v[66:67]
	v_fmamk_f32 v65, v129, 0xba000000, v65
	v_pk_fma_f32 v[122:123], v[108:109], v[108:109], v[126:127] op_sel_hi:[1,1,0]
	v_pk_fma_f32 v[126:127], v[70:71], v[70:71], v[128:129] op_sel_hi:[1,1,0]
	v_pk_add_f32 v[112:113], v[112:113], v[112:113] op_sel_hi:[0,1]
	v_pk_add_f32 v[66:67], v[66:67], v[66:67] op_sel_hi:[0,1]
	v_fmac_f32_e32 v64, 0xba000000, v129
	v_mul_f32_e32 v122, v64, v64
	v_mul_f32_e32 v126, v65, v65
	v_mul_f32_e32 v112, v110, v110
	v_mul_f32_e32 v66, v111, v111
	v_pk_add_f32 v[68:69], v[122:123], v[126:127]
	v_pk_add_f32 v[66:67], v[112:113], v[66:67]
	s_nop 0
	v_pk_add_f32 v[66:67], v[68:69], v[66:67]
	s_nop 0
	v_add_f32_e32 v66, v66, v67
	s_nop 1
	v_add_f32_dpp v66, v66, v66 quad_perm:[1,0,3,2] row_mask:0xf bank_mask:0xf
	s_nop 1
	v_add_f32_dpp v66, v66, v66 quad_perm:[2,3,0,1] row_mask:0xf bank_mask:0xf
	s_nop 1
	v_add_f32_dpp v66, v66, v66 row_half_mirror row_mask:0xf bank_mask:0xf
	s_nop 1
	v_add_f32_dpp v66, v66, v66 row_mirror row_mask:0xf bank_mask:0xf
	v_mov_b32_e32 v67, v66
	s_nop 1
	v_permlane16_swap_b32_e32 v66, v67
	v_add_f32_e32 v66, v66, v67
	v_mov_b32_e32 v67, v66
	s_nop 1
	v_permlane32_swap_b32_e32 v66, v67
	v_add_f32_e32 v66, v66, v67
	v_fmamk_f32 v66, v66, 0x3a000000, v104
	v_mul_f32_e32 v67, 0x4f800000, v66
	v_cmp_gt_f32_e32 vcc, s4, v66
	s_nop 1
	v_cndmask_b32_e32 v66, v66, v67, vcc
	v_sqrt_f32_e32 v67, v66
	s_nop 0
	v_add_u32_e32 v68, -1, v67
	v_add_u32_e32 v69, 1, v67
	v_fma_f32 v78, -v68, v67, v66
	v_fma_f32 v79, -v69, v67, v66
	v_cmp_ge_f32_e64 s[0:1], 0, v78
	s_nop 1
	v_cndmask_b32_e64 v67, v67, v68, s[0:1]
	v_cmp_lt_f32_e64 s[0:1], 0, v79
	s_nop 1
	v_cndmask_b32_e64 v67, v67, v69, s[0:1]
	v_mul_f32_e32 v68, 0x37800000, v67
	v_cndmask_b32_e32 v67, v67, v68, vcc
	v_cmp_class_f32_e32 vcc, v66, v105
	s_nop 1
	v_cndmask_b32_e32 v66, v67, v66, vcc
	v_div_scale_f32 v67, s[0:1], v66, v66, 1.0
	v_rcp_f32_e32 v68, v67
	v_div_scale_f32 v69, vcc, 1.0, v66, 1.0
	v_fma_f32 v78, -v67, v68, 1.0
	v_fmac_f32_e32 v68, v78, v68
	v_mul_f32_e32 v78, v69, v68
	v_fma_f32 v79, -v67, v78, v69
	v_fmac_f32_e32 v78, v79, v68
	v_fma_f32 v67, -v67, v78, v69
	v_div_fmas_f32 v67, v67, v68, v78
	v_div_fixup_f32 v112, v67, v66, 1.0
	v_pk_mul_f32 v[66:67], v[92:93], v[112:113] op_sel_hi:[1,0]
	v_pk_mul_f32 v[68:69], v[94:95], v[112:113] op_sel_hi:[1,0]
	v_pk_mul_f32 v[78:79], v[80:81], v[112:113] op_sel_hi:[1,0]
	v_pk_mul_f32 v[80:81], v[82:83], v[112:113] op_sel_hi:[1,0]
	v_pk_mul_f32 v[82:83], v[88:89], v[112:113] op_sel_hi:[1,0]
	v_pk_mul_f32 v[88:89], v[90:91], v[112:113] op_sel_hi:[1,0]
	v_pk_fma_f32 v[68:69], v[2:3], v[68:69], v[6:7]
	v_pk_fma_f32 v[66:67], v[0:1], v[66:67], v[4:5]
	v_pk_mul_f32 v[90:91], v[84:85], v[112:113] op_sel_hi:[1,0]
	v_pk_fma_f32 v[80:81], v[10:11], v[80:81], v[14:15]
	v_pk_fma_f32 v[78:79], v[8:9], v[78:79], v[12:13]
	v_pk_fma_f32 v[84:85], v[18:19], v[88:89], v[22:23]
	v_pk_fma_f32 v[82:83], v[16:17], v[82:83], v[20:21]
	global_store_dwordx4 v[96:97], v[66:69], off offset:-4096
	global_store_dwordx4 v[96:97], v[78:81], off offset:-3072
	global_store_dwordx4 v[96:97], v[82:85], off offset:-2048
	v_pk_mul_f32 v[66:67], v[76:77], v[112:113] op_sel_hi:[1,0]
	v_pk_mul_f32 v[68:69], v[106:107], v[112:113] op_sel_hi:[1,0]
	v_pk_fma_f32 v[66:67], v[32:33], v[66:67], v[36:37]
	v_pk_fma_f32 v[68:69], v[34:35], v[68:69], v[38:39]
	global_store_dwordx4 v[96:97], v[66:69], off
	v_pk_mul_f32 v[86:87], v[86:87], v[112:113] op_sel_hi:[1,0]
	v_pk_mul_f32 v[64:65], v[64:65], v[112:113] op_sel_hi:[1,0]
	v_pk_mul_f32 v[66:67], v[72:73], v[112:113] op_sel_hi:[1,0]
	v_pk_mul_f32 v[68:69], v[74:75], v[112:113] op_sel_hi:[1,0]
	v_pk_fma_f32 v[66:67], v[40:41], v[66:67], v[44:45]
	v_pk_fma_f32 v[68:69], v[42:43], v[68:69], v[46:47]
	global_store_dwordx4 v[96:97], v[66:69], off offset:1024
	v_pk_fma_f32 v[86:87], v[26:27], v[86:87], v[30:31]
	v_pk_fma_f32 v[84:85], v[24:25], v[90:91], v[28:29]
	v_pk_mul_f32 v[66:67], v[108:109], v[112:113] op_sel_hi:[1,0]
	v_pk_mul_f32 v[68:69], v[70:71], v[112:113] op_sel_hi:[1,0]
	v_pk_fma_f32 v[66:67], v[48:49], v[66:67], v[52:53]
	v_pk_fma_f32 v[68:69], v[50:51], v[68:69], v[54:55]
	global_store_dwordx4 v[96:97], v[66:69], off offset:2048
	v_pk_fma_f32 v[64:65], v[56:57], v[64:65], v[60:61]
	global_store_dwordx4 v[96:97], v[84:87], off offset:-1024
	v_pk_mul_f32 v[66:67], v[110:111], v[112:113] op_sel_hi:[1,0]
	s_nop 0
	v_pk_fma_f32 v[66:67], v[58:59], v[66:67], v[62:63]
	global_store_dwordx4 v[96:97], v[64:67], off offset:3072
	v_lshl_add_u64 v[96:97], v[96:97], 0, s[2:3]
	s_cbranch_scc0 .LBB0_1091
